# waiter spin back-off raised to s_sleep 16 plus LRU chunk-start output-tile stores deferred past the load waits, on top of v045
# baseline (speedup 1.0000x reference)
; __device__ __forceinline__ unsigned xb_ld(unsigned* p)              { return __hip_atomic_load(p, __ATOMIC_RELAXED, __HIP_MEMORY_SCOPE_AGENT); }
; #define XB_SPIN(cond, bar) do { unsigned _sp = 0; while (cond) { __builtin_amdgcn_s_sleep(1); \
;     if ((++_sp & 255u) == 0u) { if (xb_ld(&(bar)[XB_TMO])) break; if (_sp > XB_SPIN_CAP) { atomicAdd(&(bar)[XB_TMO], 1u); break; } } } } while (0)
; __device__ __forceinline__ void xcd_barrier(const XcdBarrier& b) {
;     ...
;             XB_SPIN(xb_ld(&bar[XB_XGEN(b.x)]) == gen, bar);
.LBB0_140:
	s_and_b32 s3, s2, 0xff
	s_mov_b64 s[42:43], -1
	s_cmp_lg_u32 s3, 0
	s_mov_b64 s[46:47], -1
	s_sleep 16
	s_cbranch_scc1 .LBB0_143
	global_load_dword v2, v0, s[12:13] sc1
	s_waitcnt vmcnt(0)
	v_cmp_eq_u32_e32 vcc, 0, v2
	s_cbranch_vccnz .LBB0_145
	s_mov_b64 s[46:47], 0
	s_mov_b64 s[44:45], -1

; __device__ __forceinline__ unsigned xb_ld(unsigned* p)              { return __hip_atomic_load(p, __ATOMIC_RELAXED, __HIP_MEMORY_SCOPE_AGENT); }
; #define XB_SPIN(cond, bar) do { unsigned _sp = 0; while (cond) { __builtin_amdgcn_s_sleep(1); \
;     if ((++_sp & 255u) == 0u) { if (xb_ld(&(bar)[XB_TMO])) break; if (_sp > XB_SPIN_CAP) { atomicAdd(&(bar)[XB_TMO], 1u); break; } } } } while (0)
; __device__ __forceinline__ void xcd_barrier(const XcdBarrier& b) {
;     ...
;             XB_SPIN(xb_ld(&bar[XB_XGEN(b.x)]) == gen, bar);
.LBB0_471:
	s_and_b32 s3, s2, 0xff
	s_mov_b64 s[46:47], -1
	s_cmp_lg_u32 s3, 0
	s_mov_b64 s[50:51], -1
	s_sleep 16
	s_cbranch_scc1 .LBB0_474
	global_load_dword v2, v0, s[12:13] sc1
	s_waitcnt vmcnt(0)
	v_cmp_eq_u32_e32 vcc, 0, v2
	s_cbranch_vccnz .LBB0_476
	s_mov_b64 s[50:51], 0
	s_mov_b64 s[48:49], -1

; __device__ __forceinline__ unsigned xb_ld(unsigned* p)              { return __hip_atomic_load(p, __ATOMIC_RELAXED, __HIP_MEMORY_SCOPE_AGENT); }
; #define XB_SPIN(cond, bar) do { unsigned _sp = 0; while (cond) { __builtin_amdgcn_s_sleep(1); \
;     if ((++_sp & 255u) == 0u) { if (xb_ld(&(bar)[XB_TMO])) break; if (_sp > XB_SPIN_CAP) { atomicAdd(&(bar)[XB_TMO], 1u); break; } } } } while (0)
; __device__ __forceinline__ void xcd_barrier(const XcdBarrier& b) {
;     ...
;             XB_SPIN(xb_ld(&bar[XB_XGEN(b.x)]) == gen, bar);
.LBB0_545:
	s_and_b32 s3, s2, 0xff
	s_mov_b64 s[44:45], -1
	s_cmp_lg_u32 s3, 0
	s_mov_b64 s[48:49], -1
	s_sleep 16
	s_cbranch_scc1 .LBB0_548
	global_load_dword v2, v0, s[12:13] sc1
	s_waitcnt vmcnt(0)
	v_cmp_eq_u32_e32 vcc, 0, v2
	s_cbranch_vccnz .LBB0_550
	s_mov_b64 s[48:49], 0
	s_mov_b64 s[46:47], -1
